# SSM phase A: latent pass-1 scan jobs spread over waves 0-3 of every workgroup instead of doubling up the first 112 workgroups
# speedup vs baseline: 1.0124x; 1.0007x over previous
.LBB0_624:
	v_lshl_add_u64 v[2:3], v[2:3], 3, s[2:3]
	s_nop 0
	global_store_dwordx2 v[2:3], v[106:107], off
	s_cmpk_lg_u32 s26, 0x100
	s_cbranch_scc1 .Lssa_orig
	s_cmpk_gt_i32 s39, 0x7ff
	s_cbranch_scc1 .LBB0_633
	s_cmp_gt_u32 s27, 3
	s_cbranch_scc1 .LBB0_633
	s_lshl_b32 s39, s27, 8
	s_add_i32 s39, s39, s43
	s_cmpk_gt_i32 s39, 0x37f
	s_cbranch_scc1 .LBB0_633
	s_addk_i32 s39, 0x800
	s_branch .LBB0_625
.Lssa_orig:
	s_add_i32 s39, s39, s96
	s_cmpk_gt_i32 s39, 0xb7f
	s_cbranch_scc1 .LBB0_633
